# stick-breaking attention: 15 redundant float canonicalizes (v_max x,x before v_max 0,x) removed; bit-identical
# speedup vs baseline: 1.0050x; 1.0050x over previous
; #define MFMA(a, b, c) __builtin_amdgcn_mfma_f32_32x32x16_bf16((a), (b), (c), 0, 0, 0)
; DI int crow(int i, int h) { return (i & 3) + 8 * (i >> 2) + 4 * h; }
; DI void qk_tile(const bf16_t* sK, const bf16x8 (&qf)[4], f32x16 (&Sx)[2], int r, int h) {
; #pragma unroll
;   for (int mt = 0; mt < 2; ++mt) {
;     f32x16 a;
; #pragma unroll
;     for (int i = 0; i < 16; ++i) a[i] = 0.f;
; #pragma unroll
;     for (int s = 0; s < 4; ++s) {
;       const bf16x8 k = *(const bf16x8*)(sK + (mt * 32 + r) * 72 + s * 16 + h * 8);
;       a = MFMA(k, qf[s], a);
;     }
;     Sx[mt] = a;
;   }
; }
; template <bool MASKED>
; DI void sb_weights(f32x16 (&Sx)[2], float& carry, int kt, int t, int h) {
; #pragma unroll
;     ...
;         float L[16];
; #pragma unroll
;         for (int i = 0; i < 16; ++i) {
;           const float z = Sx[mt][i];
;           const bool ok = !MASKED || (kt * 64 + mt * 32 + crow(i, h) < t);
;           const float sp = fmaxf(z, 0.f) + __logf(1.f + __expf(-fabsf(z)));
;           L[i] = ok ? -sp : 0.f;
;           Sx[mt][i] = ok ? (z - sp) : NEG;
;         }
; DI void sb_item(const Params& p_, int b, int hh, int qt, unsigned char* smem) {
;     ...
;     if (kt <= my_hi) {
;       f32x16 Sx[2]; qk_tile(sK, qf, Sx, r, h);
;       if (kt * 64 + 63 >= q0) sb_weights<true>(Sx, carry, kt, t, h);
.LBB0_277:
	s_add_i32 s44, s80, 1
	v_cmp_le_i32_e64 s[0:1], s44, v177
	s_and_saveexec_b64 s[36:37], s[0:1]
	s_cbranch_execz .LBB0_283
	ds_read_b128 v[0:3], v32
	ds_read_b128 v[4:7], v32 offset:32
	v_cmp_ge_i32_e64 s[0:1], s42, v175
	v_add_f32_e32 v188, 0, v144
	s_waitcnt lgkmcnt(1)
	v_mfma_f32_32x32x16_bf16 v[66:81], v[0:3], v[106:109], 0
	ds_read_b128 v[0:3], v32 offset:4608
	ds_read_b128 v[8:11], v32 offset:4640
	s_waitcnt lgkmcnt(1)
	v_mfma_f32_32x32x16_bf16 v[82:97], v[0:3], v[106:109], 0
	s_waitcnt lgkmcnt(0)
	v_mfma_f32_32x32x16_bf16 v[82:97], v[8:11], v[98:101], v[82:97]
	ds_read_b128 v[0:3], v32 offset:4672
	ds_read_b128 v[8:11], v32 offset:64
	ds_read_b128 v[12:15], v32 offset:96
	ds_read_b128 v[16:19], v32 offset:4704
	v_mfma_f32_32x32x16_bf16 v[66:81], v[4:7], v[98:101], v[66:81]
	s_waitcnt lgkmcnt(3)
	v_mfma_f32_32x32x16_bf16 v[82:97], v[0:3], v[102:105], v[82:97]
	v_and_b32_e32 v1, 64, v208
	v_xor_b32_e32 v0, 32, v208
	v_add_u32_e32 v1, 64, v1
	v_cmp_lt_i32_e64 s[4:5], v0, v1
	s_nop 1
	s_nop 0
	v_cndmask_b32_e64 v0, v208, v0, s[4:5]
	s_waitcnt lgkmcnt(2)
	v_mfma_f32_32x32x16_bf16 v[66:81], v[8:11], v[102:105], v[66:81]
	v_lshlrev_b32_e32 v181, 2, v0
	s_waitcnt lgkmcnt(0)
	v_mfma_f32_32x32x16_bf16 v[82:97], v[16:19], v[110:113], v[82:97]
	v_mfma_f32_32x32x16_bf16 v[66:81], v[12:15], v[110:113], v[66:81]
	s_nop 10
	v_mul_f32_e64 v1, |v82|, s76
	v_mul_f32_e64 v3, |v83|, s76
	v_mul_f32_e64 v17, |v84|, s76
	v_mul_f32_e64 v19, |v85|, s76
	v_mul_f32_e64 v21, |v86|, s76
	v_mul_f32_e64 v23, |v87|, s76
	v_mul_f32_e64 v25, |v88|, s76
	v_mul_f32_e64 v27, |v89|, s76
	v_mul_f32_e64 v29, |v90|, s76
	v_mul_f32_e64 v4, |v91|, s76
	v_mul_f32_e64 v6, |v92|, s76
	v_mul_f32_e64 v31, |v93|, s76
	v_mul_f32_e64 v147, |v94|, s76
	v_mul_f32_e64 v9, |v95|, s76
	v_mul_f32_e64 v11, |v96|, s76
	v_mul_f32_e64 v151, |v97|, s76
	v_mul_f32_e64 v13, |v66|, s76
	v_mul_f32_e64 v15, |v67|, s76
	v_mul_f32_e64 v155, |v68|, s76
	v_exp_f32_e32 v243, v1
	v_exp_f32_e32 v239, v3
	v_exp_f32_e32 v205, v17
	v_exp_f32_e32 v202, v19
	v_exp_f32_e32 v201, v21
	v_exp_f32_e32 v200, v23
	v_exp_f32_e32 v199, v25
	v_exp_f32_e32 v198, v27
	v_exp_f32_e32 v197, v29
	v_exp_f32_e32 v196, v4
	v_exp_f32_e32 v195, v6
	v_exp_f32_e32 v194, v31
	v_exp_f32_e32 v193, v147
	v_exp_f32_e32 v192, v9
	v_exp_f32_e32 v191, v11
	v_exp_f32_e32 v190, v151
	v_exp_f32_e32 v189, v13
	v_exp_f32_e32 v187, v15
	v_exp_f32_e32 v186, v155
	v_max_f32_e32 v0, v82, v82
	v_max_f32_e32 v2, v83, v83
	v_max_f32_e32 v16, v84, v84
	v_max_f32_e32 v18, v85, v85
	v_max_f32_e32 v20, v86, v86
	v_max_f32_e32 v22, v87, v87
	v_max_f32_e32 v24, v88, v88
	v_max_f32_e32 v26, v89, v89
	v_max_f32_e32 v28, v90, v90
	v_max_f32_e32 v30, v91, v91
	v_max_f32_e32 v5, v92, v92
	v_max_f32_e32 v7, v93, v93
	v_max_f32_e32 v8, v95, v95
	v_max_f32_e32 v10, v96, v96
	v_max_f32_e32 v12, v66, v66
	v_max_f32_e32 v14, v67, v67
	v_max_f32_e32 v160, 0, v0
	v_max_f32_e32 v158, 0, v2
	v_max_f32_e32 v156, 0, v16
	v_max_f32_e32 v154, 0, v18
	v_max_f32_e32 v152, 0, v20
	v_max_f32_e32 v150, 0, v22
	v_max_f32_e32 v148, 0, v24
	v_max_f32_e32 v146, 0, v26
	v_max_f32_e32 v172, 0, v28
	v_max_f32_e32 v170, 0, v30
	v_max_f32_e32 v173, 0, v5
	v_max_f32_e32 v171, 0, v7
	v_max_f32_e32 v168, 0, v94
	v_max_f32_e32 v166, 0, v8
	v_max_f32_e32 v169, 0, v10
	v_max_f32_e32 v167, 0, v97
	v_max_f32_e32 v162, 0, v12
	v_max_f32_e32 v164, 0, v14
	v_max_f32_e32 v163, 0, v68
	v_max_f32_e32 v165, v69, v69
	v_mul_f32_e64 v185, |v69|, s76
	v_max_f32_e32 v161, v70, v70
	v_mul_f32_e64 v184, |v70|, s76
	v_max_f32_e32 v159, v71, v71
	v_mul_f32_e64 v183, |v71|, s76
	v_max_f32_e32 v157, v72, v72
	v_mul_f32_e64 v182, |v72|, s76
	v_max_f32_e32 v155, v73, v73
	v_mul_f32_e64 v153, |v73|, s76
	v_max_f32_e32 v151, v74, v74
	v_mul_f32_e64 v149, |v74|, s76
	v_max_f32_e32 v147, v75, v75
	v_mul_f32_e64 v145, |v75|, s76
	s_and_saveexec_b64 s[4:5], s[0:1]
	s_xor_b64 s[38:39], exec, s[4:5]
	s_cbranch_execz .LBB0_280
	v_add_f32_e32 v0, 1.0, v243
	v_add_f32_e32 v2, 1.0, v239
	v_log_f32_e32 v0, v0
	v_log_f32_e32 v2, v2
	v_mul_f32_e32 v1, 0x3f317217, v0
	v_fma_f32 v1, v0, s77, -v1
	v_fmac_f32_e32 v1, 0x3377d1cf, v0
	v_fmac_f32_e32 v1, 0x3f317217, v0
	v_add_f32_e32 v3, 1.0, v205
	v_add_u32_e32 v22, s42, v176
	v_mov_b32_e32 v0, v1
	v_mul_f32_e32 v1, 0x3f317217, v2
	v_fma_f32 v1, v2, s77, -v1
	v_fmac_f32_e32 v1, 0x3377d1cf, v2
	v_log_f32_e32 v3, v3
	v_fmac_f32_e32 v1, 0x3f317217, v2
	v_add_f32_e32 v4, 1.0, v202
	v_subrev_u32_e32 v15, 63, v22
	v_mov_b32_e32 v2, v1
	v_mul_f32_e32 v1, 0x3f317217, v3
	v_fma_f32 v1, v3, s77, -v1
	v_log_f32_e32 v5, v4
	v_fmac_f32_e32 v1, 0x3377d1cf, v3
	v_fmac_f32_e32 v1, 0x3f317217, v3
	v_max_f32_e32 v161, 0, v161
	v_max_f32_e32 v159, 0, v159
	v_mov_b32_e32 v4, v1
	v_mul_f32_e32 v1, 0x3f317217, v5
	v_add_f32_e32 v3, 1.0, v201
	v_fma_f32 v1, v5, s77, -v1
	v_fmac_f32_e32 v1, 0x3377d1cf, v5
	v_fmac_f32_e32 v1, 0x3f317217, v5
	v_log_f32_e32 v3, v3
	v_max_f32_e32 v157, 0, v157
	v_mov_b32_e32 v6, v1
	v_add_f32_e32 v5, 1.0, v200
	v_mul_f32_e32 v8, 0x3f317217, v3
	v_fma_f32 v8, v3, s77, -v8
	v_log_f32_e32 v5, v5
	v_fmac_f32_e32 v8, 0x3377d1cf, v3
	v_fmac_f32_e32 v8, 0x3f317217, v3
	v_max_f32_e32 v155, 0, v155
	v_mul_f32_e32 v10, 0x3f317217, v5
	v_add_f32_e32 v3, 1.0, v199
	v_fma_f32 v10, v5, s77, -v10
	v_fmac_f32_e32 v10, 0x3377d1cf, v5
	v_fmac_f32_e32 v10, 0x3f317217, v5
	v_log_f32_e32 v3, v3
	v_add_f32_e32 v5, 1.0, v198
	v_mul_f32_e32 v16, 0x3f317217, v3
	v_fma_f32 v16, v3, s77, -v16
	v_log_f32_e32 v5, v5
	v_fmac_f32_e32 v16, 0x3377d1cf, v3
	v_fmac_f32_e32 v16, 0x3f317217, v3
	v_mul_f32_e32 v18, 0x3f317217, v5
	v_fma_f32 v18, v5, s77, -v18
	v_fmac_f32_e32 v18, 0x3377d1cf, v5
; DI int crow(int i, int h) { return (i & 3) + 8 * (i >> 2) + 4 * h; }
; DI float shx32(float v) { return __shfl_xor(v, 32); }
; template <bool MASKED>
; DI void sb_weights(f32x16 (&Sx)[2], float& carry, int kt, int t, int h) {
;     ...
;         for (int i = 0; i < 16; ++i) {
;           const float z = Sx[mt][i];
;           const bool ok = !MASKED || (kt * 64 + mt * 32 + crow(i, h) < t);
;           const float sp = fmaxf(z, 0.f) + __logf(1.f + __expf(-fabsf(z)));
;           L[i] = ok ? -sp : 0.f;
;           Sx[mt][i] = ok ? (z - sp) : NEG;
;         }
;         float G[4], Go[4];
; #pragma unroll
;         for (int gg = 0; gg < 4; ++gg) { G[gg] = (L[4 * gg] + L[4 * gg + 1]) + (L[4 * gg + 2] + L[4 * gg + 3]); Go[gg] = shx32(G[gg]); }
;         float T[4];
;         T[3] = 0.f; T[2] = G[3] + Go[3]; T[1] = T[2] + (G[2] + Go[2]); T[0] = T[1] + (G[1] + Go[1]);
;         const float tot = T[0] + (G[0] + Go[0]);
; #pragma unroll
;         for (int gg = 0; gg < 4; ++gg) {
;           const float s3 = carry + T[gg] + (h ? 0.f : Go[gg]);
;           const float s2 = s3 + L[4 * gg + 3], s1 = s2 + L[4 * gg + 2], s0 = s1 + L[4 * gg + 1];
;           Sx[mt][4 * gg + 3] = __expf(Sx[mt][4 * gg + 3] + s3);
;           Sx[mt][4 * gg + 2] = __expf(Sx[mt][4 * gg + 2] + s2);
;           Sx[mt][4 * gg + 1] = __expf(Sx[mt][4 * gg + 1] + s1);
;           Sx[mt][4 * gg + 0] = __expf(Sx[mt][4 * gg + 0] + s0);
;         }
	v_fmac_f32_e32 v18, 0x3f317217, v5
	v_add_f32_e32 v3, 1.0, v197
	v_log_f32_e32 v3, v3
	v_add_u32_e32 v1, -15, v22
	v_mul_f32_e32 v5, 0x3f317217, v3
	v_fma_f32 v5, v3, s77, -v5
	v_fmac_f32_e32 v5, 0x3377d1cf, v3
	v_fmac_f32_e32 v5, 0x3f317217, v3
	v_mov_b32_e32 v3, v5
	v_add_f32_e32 v5, 1.0, v196
	v_add_f32_e32 v3, v172, v3
	v_cmp_lt_i32_e64 s[0:1], v1, v130
	v_log_f32_e32 v5, v5
	s_nop 0
	v_cndmask_b32_e64 v1, 0, -v3, s[0:1]
	v_sub_f32_e32 v3, v90, v3
	v_cndmask_b32_e64 v24, v214, v3, s[0:1]
	v_mul_f32_e32 v7, 0x3f317217, v5
	v_fma_f32 v7, v5, s77, -v7
	v_fmac_f32_e32 v7, 0x3377d1cf, v5
	v_add_u32_e32 v3, -14, v22
	v_fmac_f32_e32 v7, 0x3f317217, v5
	v_cmp_lt_i32_e64 s[0:1], v3, v130
	v_add_f32_e32 v3, 1.0, v195
	v_mov_b32_e32 v5, v7
	v_add_f32_e32 v5, v170, v5
	v_log_f32_e32 v3, v3
	v_cndmask_b32_e64 v25, 0, -v5, s[0:1]
	v_sub_f32_e32 v5, v91, v5
	v_cndmask_b32_e64 v90, v214, v5, s[0:1]
	v_mul_f32_e32 v7, 0x3f317217, v3
	v_fma_f32 v7, v3, s77, -v7
	v_fmac_f32_e32 v7, 0x3377d1cf, v3
	v_add_u32_e32 v5, -13, v22
	v_fmac_f32_e32 v7, 0x3f317217, v3
	v_add_f32_e32 v20, v1, v25
	v_cmp_lt_i32_e64 s[0:1], v5, v130
	v_add_f32_e32 v5, 1.0, v194
	v_mov_b32_e32 v3, v7
	v_add_f32_e32 v3, v173, v3
	v_log_f32_e32 v5, v5
	v_cndmask_b32_e64 v26, 0, -v3, s[0:1]
	v_sub_f32_e32 v3, v92, v3
	v_cndmask_b32_e64 v91, v214, v3, s[0:1]
	v_mul_f32_e32 v7, 0x3f317217, v5
	v_fma_f32 v7, v5, s77, -v7
	v_fmac_f32_e32 v7, 0x3377d1cf, v5
	v_add_u32_e32 v3, -12, v22
	v_fmac_f32_e32 v7, 0x3f317217, v5
	v_cmp_lt_i32_e64 s[0:1], v3, v130
	v_add_f32_e32 v3, 1.0, v193
	v_mov_b32_e32 v5, v7
	v_add_f32_e32 v5, v171, v5
	v_log_f32_e32 v3, v3
	v_cndmask_b32_e64 v27, 0, -v5, s[0:1]
	v_sub_f32_e32 v5, v93, v5
	v_cndmask_b32_e64 v92, v214, v5, s[0:1]
	v_mul_f32_e32 v7, 0x3f317217, v3
	v_fma_f32 v7, v3, s77, -v7
	v_fmac_f32_e32 v7, 0x3377d1cf, v3
	v_fmac_f32_e32 v7, 0x3f317217, v3
	v_add_u32_e32 v5, -7, v22
	v_mov_b32_e32 v3, v7
	v_add_f32_e32 v7, 1.0, v192
	v_add_f32_e32 v3, v168, v3
	v_cmp_lt_i32_e64 s[0:1], v5, v130
	v_log_f32_e32 v7, v7
	s_nop 0
	v_cndmask_b32_e64 v5, 0, -v3, s[0:1]
	v_sub_f32_e32 v3, v94, v3
	v_cndmask_b32_e64 v3, v214, v3, s[0:1]
	v_mul_f32_e32 v11, 0x3f317217, v7
	v_fma_f32 v11, v7, s77, -v11
	v_fmac_f32_e32 v11, 0x3377d1cf, v7
	v_fmac_f32_e32 v11, 0x3f317217, v7
	v_add_u32_e32 v9, -6, v22
	v_mov_b32_e32 v7, v11
	v_add_f32_e32 v11, 1.0, v191
	v_add_f32_e32 v7, v166, v7
	v_cmp_lt_i32_e64 s[0:1], v9, v130
	v_log_f32_e32 v11, v11
	s_nop 0
	v_cndmask_b32_e64 v9, 0, -v7, s[0:1]
	v_sub_f32_e32 v7, v95, v7
	v_cndmask_b32_e64 v7, v214, v7, s[0:1]
	v_mul_f32_e32 v13, 0x3f317217, v11
	v_fma_f32 v13, v11, s77, -v13
	v_fmac_f32_e32 v13, 0x3377d1cf, v11
	v_add_u32_e32 v12, -5, v22
	v_fmac_f32_e32 v13, 0x3f317217, v11
	v_add_f32_e32 v5, v5, v9
	v_cmp_lt_i32_e64 s[0:1], v12, v130
	v_add_f32_e32 v12, 1.0, v190
	v_mov_b32_e32 v11, v13
	v_add_f32_e32 v11, v169, v11
	v_log_f32_e32 v12, v12
	v_cndmask_b32_e64 v13, 0, -v11, s[0:1]
	v_sub_f32_e32 v11, v96, v11
	v_cndmask_b32_e64 v11, v214, v11, s[0:1]
	v_mul_f32_e32 v17, 0x3f317217, v12
	v_fma_f32 v17, v12, s77, -v17
	v_fmac_f32_e32 v17, 0x3377d1cf, v12
	v_fmac_f32_e32 v17, 0x3f317217, v12
	v_add_u32_e32 v14, -4, v22
	v_mov_b32_e32 v12, v17
	v_add_f32_e32 v12, v167, v12
	v_cmp_lt_i32_e64 s[0:1], v14, v130
	s_nop 1
	s_nop 0
	v_cndmask_b32_e64 v17, 0, -v12, s[0:1]
	v_add_f32_e32 v14, v13, v17
	v_add_f32_e32 v5, v5, v14
	ds_bpermute_b32 v19, v181, v5
	v_sub_f32_e32 v12, v97, v12
	v_cndmask_b32_e64 v21, v214, v12, s[0:1]
	v_max_f32_e32 v97, 0, v78
	s_waitcnt lgkmcnt(0)
	v_cndmask_b32_e32 v1, 0, v19, vcc
	v_add_f32_e32 v1, v188, v1
	v_add_f32_e32 v14, v5, v19
	v_add_f32_e32 v5, v17, v1
	v_add_f32_e32 v1, v21, v1
	v_mul_f32_e32 v1, 0x3fb8aa3b, v1
	v_exp_f32_e32 v31, v1
	v_add_f32_e32 v1, v11, v5
	v_add_f32_e32 v13, v13, v5
	v_mul_f32_e32 v1, 0x3fb8aa3b, v1
	v_exp_f32_e32 v30, v1
	v_add_f32_e32 v1, v7, v13
	v_mul_f32_e32 v1, 0x3fb8aa3b, v1
	v_exp_f32_e32 v29, v1
	v_add_f32_e32 v1, 1.0, v189
	v_add_f32_e32 v9, v9, v13
	v_add_f32_e32 v3, v3, v9
	v_log_f32_e32 v1, v1
	v_mul_f32_e32 v3, 0x3fb8aa3b, v3
	v_exp_f32_e32 v28, v3
	v_exp_f32_e32 v9, v153
	v_mul_f32_e32 v3, 0x3f317217, v1
	v_fma_f32 v3, v1, s77, -v3
	v_fmac_f32_e32 v3, 0x3377d1cf, v1
	v_fmac_f32_e32 v3, 0x3f317217, v1
	v_exp_f32_e32 v11, v149
	v_exp_f32_e32 v13, v145
	v_mov_b32_e32 v1, v3
	v_add_f32_e32 v3, 1.0, v187
	v_add_f32_e32 v1, v162, v1
	v_cmp_lt_i32_e64 s[0:1], v15, v130
	v_log_f32_e32 v3, v3
	s_nop 0
	v_cndmask_b32_e64 v23, 0, -v1, s[0:1]
	v_sub_f32_e32 v1, v66, v1
	v_cndmask_b32_e64 v66, v214, v1, s[0:1]
	v_mul_f32_e32 v5, 0x3f317217, v3
	v_fma_f32 v5, v3, s77, -v5
	v_fmac_f32_e32 v5, 0x3377d1cf, v3
	v_subrev_u32_e32 v1, 62, v22
	v_fmac_f32_e32 v5, 0x3f317217, v3
	v_mul_f32_e64 v17, |v76|, s76
	v_exp_f32_e32 v17, v17
	v_cmp_lt_i32_e64 s[0:1], v1, v130
	v_add_f32_e32 v1, 1.0, v186
	v_mov_b32_e32 v3, v5
	v_add_f32_e32 v3, v164, v3
	v_log_f32_e32 v1, v1
	v_cndmask_b32_e64 v94, 0, -v3, s[0:1]
	v_sub_f32_e32 v3, v67, v3
	v_cndmask_b32_e64 v67, v214, v3, s[0:1]
	v_mul_f32_e32 v5, 0x3f317217, v1
	v_fma_f32 v5, v1, s77, -v5
	v_fmac_f32_e32 v5, 0x3377d1cf, v1
	v_fmac_f32_e32 v5, 0x3f317217, v1
	v_subrev_u32_e32 v3, 61, v22
	v_add_f32_e32 v17, 1.0, v17
	v_mov_b32_e32 v1, v5
	v_exp_f32_e32 v5, v185
	v_cmp_lt_i32_e64 s[0:1], v3, v130
	v_add_f32_e32 v1, v163, v1
	v_max_f32_e32 v153, 0, v151
	v_add_f32_e32 v3, 1.0, v5
	v_cndmask_b32_e64 v95, 0, -v1, s[0:1]
	v_sub_f32_e32 v1, v68, v1
	v_log_f32_e32 v3, v3
	v_cndmask_b32_e64 v68, v214, v1, s[0:1]
	v_subrev_u32_e32 v1, 60, v22
	v_max_f32_e32 v5, 0, v165
	v_mul_f32_e32 v7, 0x3f317217, v3
	v_fma_f32 v7, v3, s77, -v7
	v_fmac_f32_e32 v7, 0x3377d1cf, v3
; DI int crow(int i, int h) { return (i & 3) + 8 * (i >> 2) + 4 * h; }
; DI float shx32(float v) { return __shfl_xor(v, 32); }
; template <bool MASKED>
; DI void sb_weights(f32x16 (&Sx)[2], float& carry, int kt, int t, int h) {
;     ...
;         for (int i = 0; i < 16; ++i) {
;           const float z = Sx[mt][i];
;           const bool ok = !MASKED || (kt * 64 + mt * 32 + crow(i, h) < t);
;           const float sp = fmaxf(z, 0.f) + __logf(1.f + __expf(-fabsf(z)));
;           L[i] = ok ? -sp : 0.f;
;           Sx[mt][i] = ok ? (z - sp) : NEG;
;         }
;         float G[4], Go[4];
; #pragma unroll
;         for (int gg = 0; gg < 4; ++gg) { G[gg] = (L[4 * gg] + L[4 * gg + 1]) + (L[4 * gg + 2] + L[4 * gg + 3]); Go[gg] = shx32(G[gg]); }
;         float T[4];
;         T[3] = 0.f; T[2] = G[3] + Go[3]; T[1] = T[2] + (G[2] + Go[2]); T[0] = T[1] + (G[1] + Go[1]);
	v_fmac_f32_e32 v7, 0x3f317217, v3
	v_max_f32_e32 v151, 0, v147
	v_add_f32_e32 v23, v23, v94
	v_mov_b32_e32 v3, v7
	v_exp_f32_e32 v7, v184
	v_cmp_lt_i32_e64 s[0:1], v1, v130
	v_add_f32_e32 v3, v5, v3
	v_add_f32_e32 v12, v26, v27
	v_add_f32_e32 v1, 1.0, v7
	v_cndmask_b32_e64 v96, 0, -v3, s[0:1]
	v_sub_f32_e32 v3, v69, v3
	v_log_f32_e32 v1, v1
	v_cndmask_b32_e64 v69, v214, v3, s[0:1]
	v_exp_f32_e32 v5, v183
	v_exp_f32_e32 v7, v182
	v_mul_f32_e32 v3, 0x3f317217, v1
	v_fma_f32 v3, v1, s77, -v3
	v_fmac_f32_e32 v3, 0x3377d1cf, v1
	v_fmac_f32_e32 v3, 0x3f317217, v1
	v_add_f32_e32 v93, v144, v14
	v_mov_b32_e32 v1, v3
	v_add_f32_e32 v3, 1.0, v5
	v_log_f32_e32 v3, v3
	v_mov_b32_e32 v1, v1
	v_pk_add_f32 v[0:1], v[160:161], v[0:1]
	v_mul_f32_e32 v5, 0x3f317217, v3
	v_fma_f32 v5, v3, s77, -v5
	v_fmac_f32_e32 v5, 0x3377d1cf, v3
	v_fmac_f32_e32 v5, 0x3f317217, v3
	v_mov_b32_e32 v3, v5
	v_add_f32_e32 v5, 1.0, v7
	v_log_f32_e32 v5, v5
	v_mov_b32_e32 v3, v3
	v_pk_add_f32 v[2:3], v[158:159], v[2:3]
	v_mul_f32_e32 v7, 0x3f317217, v5
	v_fma_f32 v7, v5, s77, -v7
	v_fmac_f32_e32 v7, 0x3377d1cf, v5
	v_fmac_f32_e32 v7, 0x3f317217, v5
	v_mov_b32_e32 v5, v7
	v_add_f32_e32 v7, 1.0, v9
	v_log_f32_e32 v7, v7
	v_mov_b32_e32 v5, v5
	v_pk_add_f32 v[4:5], v[156:157], v[4:5]
	v_mul_f32_e32 v9, 0x3f317217, v7
	v_fma_f32 v9, v7, s77, -v9
	v_fmac_f32_e32 v9, 0x3377d1cf, v7
	v_fmac_f32_e32 v9, 0x3f317217, v7
	v_or_b32_e32 v156, 10, v15
	v_mov_b32_e32 v7, v9
	v_add_f32_e32 v9, 1.0, v11
	v_log_f32_e32 v9, v9
	v_mov_b32_e32 v7, v7
	v_pk_add_f32 v[6:7], v[154:155], v[6:7]
	v_mul_f32_e32 v11, 0x3f317217, v9
	v_fma_f32 v11, v9, s77, -v11
	v_fmac_f32_e32 v11, 0x3377d1cf, v9
	v_fmac_f32_e32 v11, 0x3f317217, v9
	v_or_b32_e32 v154, 11, v15
	v_mov_b32_e32 v9, v11
	v_add_f32_e32 v11, 1.0, v13
	v_log_f32_e32 v11, v11
	v_mov_b32_e32 v9, v9
	v_pk_add_f32 v[8:9], v[152:153], v[8:9]
	v_mul_f32_e32 v13, 0x3f317217, v11
	v_fma_f32 v13, v11, s77, -v13
	v_fmac_f32_e32 v13, 0x3377d1cf, v11
	v_fmac_f32_e32 v13, 0x3f317217, v11
	v_or_b32_e32 v152, 16, v15
	v_mov_b32_e32 v11, v13
	v_log_f32_e32 v17, v17
	v_mul_f32_e64 v19, |v77|, s76
	v_exp_f32_e32 v19, v19
	v_max_f32_e32 v149, 0, v76
	v_mul_f32_e32 v13, 0x3f317217, v17
	v_fma_f32 v13, v17, s77, -v13
	v_fmac_f32_e32 v13, 0x3377d1cf, v17
	v_fmac_f32_e32 v13, 0x3f317217, v17
	v_add_f32_e32 v19, 1.0, v19
	v_pk_add_f32 v[10:11], v[150:151], v[10:11]
	v_mov_b32_e32 v17, v13
	v_log_f32_e32 v19, v19
	v_max_f32_e32 v147, 0, v77
	v_mul_f32_e64 v21, |v78|, s76
	v_exp_f32_e32 v21, v21
	v_mul_f32_e32 v13, 0x3f317217, v19
	v_fma_f32 v13, v19, s77, -v13
	v_fmac_f32_e32 v13, 0x3377d1cf, v19
	v_fmac_f32_e32 v13, 0x3f317217, v19
	v_or_b32_e32 v150, 17, v15
	v_or_b32_e32 v151, 19, v15
	v_mov_b32_e32 v19, v13
	v_add_f32_e32 v13, 1.0, v21
	v_log_f32_e32 v13, v13
	v_subrev_u32_e32 v21, 39, v22
	v_mul_f32_e32 v145, 0x3f317217, v13
	v_fma_f32 v145, v13, s77, -v145
	v_fmac_f32_e32 v145, 0x3377d1cf, v13
	v_fmac_f32_e32 v145, 0x3f317217, v13
	v_mov_b32_e32 v13, v145
	v_add_f32_e32 v13, v97, v13
	v_mul_f32_e64 v97, |v79|, s76
	v_exp_f32_e32 v97, v97
	v_cmp_lt_i32_e64 s[0:1], v21, v130
	s_nop 1
	s_nop 0
	v_cndmask_b32_e64 v21, 0, -v13, s[0:1]
	v_sub_f32_e32 v13, v78, v13
	v_cndmask_b32_e64 v162, v214, v13, s[0:1]
	v_add_f32_e32 v13, 1.0, v97
	v_max_f32_e32 v97, 0, v79
	v_log_f32_e32 v13, v13
	v_subrev_u32_e32 v78, 38, v22
	v_mul_f32_e32 v145, 0x3f317217, v13
	v_fma_f32 v145, v13, s77, -v145
	v_fmac_f32_e32 v145, 0x3377d1cf, v13
	v_fmac_f32_e32 v145, 0x3f317217, v13
	v_mov_b32_e32 v13, v145
	v_add_f32_e32 v97, v97, v13
	v_mul_f32_e64 v13, |v80|, s76
	v_exp_f32_e32 v145, v13
	v_cmp_lt_i32_e64 s[0:1], v78, v130
	v_sub_f32_e32 v78, v79, v97
	s_nop 0
	v_cndmask_b32_e64 v13, 0, -v97, s[0:1]
	v_cndmask_b32_e64 v97, v214, v78, s[0:1]
	v_add_f32_e32 v78, 1.0, v145
	v_max_f32_e32 v145, 0, v80
	v_log_f32_e32 v78, v78
	v_subrev_u32_e32 v79, 37, v22
	v_subrev_u32_e32 v22, 36, v22
	v_pk_add_f32 v[20:21], v[20:21], v[12:13]
	v_mul_f32_e32 v163, 0x3f317217, v78
	v_fma_f32 v163, v78, s77, -v163
	v_fmac_f32_e32 v163, 0x3377d1cf, v78
	v_fmac_f32_e32 v163, 0x3f317217, v78
	v_mov_b32_e32 v78, v163
	v_add_f32_e32 v78, v145, v78
	v_mul_f32_e64 v145, |v81|, s76
	v_exp_f32_e32 v145, v145
	v_cmp_lt_i32_e64 s[0:1], v79, v130
	s_nop 1
	s_nop 0
	v_cndmask_b32_e64 v163, 0, -v78, s[0:1]
	v_sub_f32_e32 v78, v80, v78
	v_cndmask_b32_e64 v164, v214, v78, s[0:1]
	v_add_f32_e32 v78, 1.0, v145
	v_log_f32_e32 v78, v78
	v_max_f32_e32 v79, 0, v81
	v_mul_f32_e32 v80, 0x3f317217, v78
	v_fma_f32 v80, v78, s77, -v80
	v_fmac_f32_e32 v80, 0x3377d1cf, v78
	v_fmac_f32_e32 v80, 0x3f317217, v78
	v_mov_b32_e32 v78, v80
	v_add_f32_e32 v78, v79, v78
	v_add_f32_e32 v79, v95, v96
	v_add_f32_e32 v23, v23, v79
	ds_bpermute_b32 v80, v181, v23
	v_cmp_lt_i32_e64 s[0:1], v22, v130
	v_sub_f32_e32 v22, v81, v78
	s_waitcnt lgkmcnt(0)
; DI int crow(int i, int h) { return (i & 3) + 8 * (i >> 2) + 4 * h; }
; DI float shx32(float v) { return __shfl_xor(v, 32); }
; template <bool MASKED>
; DI void sb_weights(f32x16 (&Sx)[2], float& carry, int kt, int t, int h) {
;     ...
;           const float z = Sx[mt][i];
;           const bool ok = !MASKED || (kt * 64 + mt * 32 + crow(i, h) < t);
;           const float sp = fmaxf(z, 0.f) + __logf(1.f + __expf(-fabsf(z)));
;           L[i] = ok ? -sp : 0.f;
;           Sx[mt][i] = ok ? (z - sp) : NEG;
;         }
;         float G[4], Go[4];
; #pragma unroll
;         for (int gg = 0; gg < 4; ++gg) { G[gg] = (L[4 * gg] + L[4 * gg + 1]) + (L[4 * gg + 2] + L[4 * gg + 3]); Go[gg] = shx32(G[gg]); }
;         float T[4];
;         T[3] = 0.f; T[2] = G[3] + Go[3]; T[1] = T[2] + (G[2] + Go[2]); T[0] = T[1] + (G[1] + Go[1]);
;         const float tot = T[0] + (G[0] + Go[0]);
; #pragma unroll
;         for (int gg = 0; gg < 4; ++gg) {
;           const float s3 = carry + T[gg] + (h ? 0.f : Go[gg]);
;           const float s2 = s3 + L[4 * gg + 3], s1 = s2 + L[4 * gg + 2], s0 = s1 + L[4 * gg + 1];
;           Sx[mt][4 * gg + 3] = __expf(Sx[mt][4 * gg + 3] + s3);
;           Sx[mt][4 * gg + 2] = __expf(Sx[mt][4 * gg + 2] + s2);
;           Sx[mt][4 * gg + 1] = __expf(Sx[mt][4 * gg + 1] + s1);
;           Sx[mt][4 * gg + 0] = __expf(Sx[mt][4 * gg + 0] + s0);
;         }
;         carry += tot;
	v_add_f32_e32 v145, v23, v80
	v_cndmask_b32_e64 v165, 0, -v78, s[0:1]
	v_or_b32_e32 v78, 32, v15
	v_cndmask_b32_e64 v166, v214, v22, s[0:1]
	v_cndmask_b32_e32 v167, 0, v80, vcc
	v_sub_f32_e32 v22, v82, v0
	v_cmp_lt_i32_e64 s[4:5], v78, v130
	v_or_b32_e32 v80, 33, v15
	v_cmp_lt_i32_e64 s[6:7], v80, v130
	v_cndmask_b32_e64 v168, v214, v22, s[4:5]
	v_sub_f32_e32 v22, v83, v2
	v_or_b32_e32 v80, 34, v15
	v_cndmask_b32_e64 v169, v214, v22, s[6:7]
	v_sub_f32_e32 v22, v84, v4
	v_cmp_lt_i32_e64 s[8:9], v80, v130
	v_or_b32_e32 v80, 35, v15
	v_cmp_lt_i32_e64 s[10:11], v80, v130
	v_cndmask_b32_e64 v170, v214, v22, s[8:9]
	v_sub_f32_e32 v22, v85, v6
	v_or_b32_e32 v80, 40, v15
	v_cndmask_b32_e64 v171, v214, v22, s[10:11]
	v_sub_f32_e32 v22, v86, v8
	v_cmp_lt_i32_e64 s[12:13], v80, v130
	v_or_b32_e32 v80, 41, v15
	v_cmp_lt_i32_e64 s[14:15], v80, v130
	v_cndmask_b32_e64 v172, v214, v22, s[12:13]
	v_sub_f32_e32 v22, v87, v10
	v_pk_add_f32 v[80:81], v[148:149], v[16:17]
	v_or_b32_e32 v17, 42, v15
	v_or_b32_e32 v23, 8, v15
	v_or_b32_e32 v78, 9, v15
	v_cndmask_b32_e64 v173, v214, v22, s[14:15]
	v_sub_f32_e32 v16, v88, v80
	v_or_b32_e32 v22, 18, v15
	v_cmp_lt_i32_e64 s[16:17], v17, v130
	v_pk_add_f32 v[82:83], v[146:147], v[18:19]
	v_or_b32_e32 v15, 43, v15
	v_cndmask_b32_e64 v182, v214, v16, s[16:17]
	v_sub_f32_e32 v16, v89, v82
	v_cmp_lt_i32_e64 s[18:19], v15, v130
	v_cndmask_b32_e64 v88, 0, -v6, s[10:11]
	v_cmp_lt_i32_e64 s[10:11], v152, v131
	v_cndmask_b32_e64 v183, v214, v16, s[18:19]
	v_cndmask_b32_e64 v16, 0, -v0, s[4:5]
	v_cmp_lt_i32_e64 s[4:5], v78, v131
	ds_bpermute_b32 v78, v181, v20
	v_cndmask_b32_e64 v18, 0, -v8, s[12:13]
	v_cmp_lt_i32_e64 s[12:13], v150, v131
	v_cndmask_b32_e64 v146, 0, -v10, s[14:15]
	v_cmp_lt_i32_e64 s[14:15], v22, v131
	v_cndmask_b32_e64 v148, 0, -v80, s[16:17]
	v_cmp_lt_i32_e64 s[16:17], v151, v131
	v_cndmask_b32_e64 v19, 0, -v9, s[10:11]
	v_cndmask_b32_e64 v147, 0, -v11, s[12:13]
	v_cndmask_b32_e64 v149, 0, -v81, s[14:15]
	v_cndmask_b32_e64 v151, 0, -v83, s[16:17]
	v_cndmask_b32_e64 v150, 0, -v82, s[18:19]
	v_add_f32_e32 v79, v163, v165
	v_cmp_lt_i32_e64 s[0:1], v23, v131
	v_cndmask_b32_e64 v84, 0, -v2, s[6:7]
	v_cmp_lt_i32_e64 s[6:7], v156, v131
	v_cndmask_b32_e64 v86, 0, -v4, s[8:9]
	v_cmp_lt_i32_e64 s[8:9], v154, v131
	v_pk_add_f32 v[18:19], v[18:19], v[146:147]
	v_pk_add_f32 v[22:23], v[148:149], v[150:151]
	v_cndmask_b32_e64 v17, 0, -v1, s[0:1]
	v_cndmask_b32_e64 v85, 0, -v3, s[4:5]
	v_cndmask_b32_e64 v87, 0, -v5, s[6:7]
	v_cndmask_b32_e64 v89, 0, -v7, s[8:9]
	v_pk_add_f32 v[18:19], v[18:19], v[22:23]
	s_waitcnt lgkmcnt(0)
	v_pk_add_f32 v[20:21], v[20:21], v[78:79]
	v_pk_add_f32 v[16:17], v[16:17], v[84:85]
	ds_bpermute_b32 v152, v181, v18
	ds_bpermute_b32 v15, v181, v21
	ds_bpermute_b32 v153, v181, v19
	v_pk_add_f32 v[22:23], v[86:87], v[88:89]
	s_waitcnt lgkmcnt(1)
	v_pk_add_f32 v[158:159], v[20:21], v[14:15]
	v_pk_add_f32 v[154:155], v[16:17], v[22:23]
	ds_bpermute_b32 v156, v181, v154
	s_waitcnt lgkmcnt(1)
	v_pk_add_f32 v[16:17], v[18:19], v[152:153]
	ds_bpermute_b32 v157, v181, v155
	v_pk_add_f32 v[160:161], v[16:17], v[158:159]
	s_waitcnt lgkmcnt(1)
	v_cndmask_b32_e32 v2, 0, v156, vcc
	v_add_f32_e32 v0, v144, v160
	v_add_f32_e32 v0, v2, v0
	v_add_f32_e32 v2, v88, v0
	v_add_f32_e32 v0, v171, v0
	v_mul_f32_e32 v0, 0x3fb8aa3b, v0
	v_exp_f32_e32 v19, v0
	v_add_f32_e32 v0, v170, v2
	v_add_f32_e32 v4, v86, v2
	v_mul_f32_e32 v0, 0x3fb8aa3b, v0
	v_exp_f32_e32 v18, v0
	v_add_f32_e32 v0, v169, v4
	v_add_f32_e32 v6, v84, v4
	v_mul_f32_e32 v0, 0x3fb8aa3b, v0
	v_exp_f32_e32 v17, v0
	v_add_f32_e32 v0, v168, v6
	v_mul_f32_e32 v0, 0x3fb8aa3b, v0
	v_exp_f32_e32 v16, v0
	v_add_f32_e32 v0, v144, v158
	v_cndmask_b32_e32 v2, 0, v152, vcc
	v_add_f32_e32 v0, v2, v0
	v_add_f32_e32 v2, v150, v0
	v_add_f32_e32 v0, v183, v0
	v_mul_f32_e32 v0, 0x3fb8aa3b, v0
	v_exp_f32_e32 v23, v0
	v_add_f32_e32 v0, v182, v2
	v_add_f32_e32 v4, v148, v2
	v_mul_f32_e32 v0, 0x3fb8aa3b, v0
	v_exp_f32_e32 v22, v0
	v_add_f32_e32 v0, v173, v4
	v_add_f32_e32 v6, v146, v4
	v_mul_f32_e32 v0, 0x3fb8aa3b, v0
	v_exp_f32_e32 v21, v0
	v_add_f32_e32 v0, v172, v6
	v_mul_f32_e32 v0, 0x3fb8aa3b, v0
	v_exp_f32_e32 v20, v0
	v_cndmask_b32_e32 v0, 0, v78, vcc
	v_add_f32_e32 v0, v0, v93
	v_add_f32_e32 v2, v27, v0
	v_add_f32_e32 v0, v92, v0
	v_mul_f32_e32 v0, 0x3fb8aa3b, v0
	v_exp_f32_e32 v27, v0
	v_add_f32_e32 v0, v91, v2
	v_add_f32_e32 v4, v26, v2
	v_mul_f32_e32 v0, 0x3fb8aa3b, v0
	v_exp_f32_e32 v26, v0
	v_add_f32_e32 v0, v90, v4
	v_add_f32_e32 v6, v25, v4
	v_mul_f32_e32 v0, 0x3fb8aa3b, v0
	v_exp_f32_e32 v25, v0
	v_add_f32_e32 v0, v24, v6
	v_mul_f32_e32 v0, 0x3fb8aa3b, v0
	v_exp_f32_e32 v24, v0
	v_sub_f32_e32 v0, v70, v1
	v_cndmask_b32_e64 v4, v214, v0, s[0:1]
	v_sub_f32_e32 v0, v71, v3
	v_cndmask_b32_e64 v8, v214, v0, s[4:5]
	v_sub_f32_e32 v0, v72, v5
	v_cndmask_b32_e64 v5, v214, v0, s[6:7]
	v_sub_f32_e32 v0, v73, v7
	v_cndmask_b32_e64 v6, v214, v0, s[8:9]
	v_sub_f32_e32 v0, v74, v9
	v_cndmask_b32_e64 v12, v214, v0, s[10:11]
	v_sub_f32_e32 v0, v75, v11
	v_cndmask_b32_e64 v9, v214, v0, s[12:13]
	v_sub_f32_e32 v0, v76, v81
	v_cndmask_b32_e64 v10, v214, v0, s[14:15]
	v_sub_f32_e32 v0, v77, v83
	v_cndmask_b32_e64 v11, v214, v0, s[16:17]
	s_waitcnt lgkmcnt(0)
; DI int crow(int i, int h) { return (i & 3) + 8 * (i >> 2) + 4 * h; }
; DI float shx32(float v) { return __shfl_xor(v, 32); }
; template <bool MASKED>
; DI void sb_weights(f32x16 (&Sx)[2], float& carry, int kt, int t, int h) {
;     ...
;         float L[16];
; #pragma unroll
;         for (int i = 0; i < 16; ++i) {
;           const float z = Sx[mt][i];
;           const bool ok = !MASKED || (kt * 64 + mt * 32 + crow(i, h) < t);
;           const float sp = fmaxf(z, 0.f) + __logf(1.f + __expf(-fabsf(z)));
;           L[i] = ok ? -sp : 0.f;
;           Sx[mt][i] = ok ? (z - sp) : NEG;
;         }
;         float G[4], Go[4];
; #pragma unroll
;         for (int gg = 0; gg < 4; ++gg) { G[gg] = (L[4 * gg] + L[4 * gg + 1]) + (L[4 * gg + 2] + L[4 * gg + 3]); Go[gg] = shx32(G[gg]); }
;     ...
;         T[3] = 0.f; T[2] = G[3] + Go[3]; T[1] = T[2] + (G[2] + Go[2]); T[0] = T[1] + (G[1] + Go[1]);
;         const float tot = T[0] + (G[0] + Go[0]);
; #pragma unroll
;         for (int gg = 0; gg < 4; ++gg) {
;           const float s3 = carry + T[gg] + (h ? 0.f : Go[gg]);
;           const float s2 = s3 + L[4 * gg + 3], s1 = s2 + L[4 * gg + 2], s0 = s1 + L[4 * gg + 1];
;           Sx[mt][4 * gg + 3] = __expf(Sx[mt][4 * gg + 3] + s3);
;           Sx[mt][4 * gg + 2] = __expf(Sx[mt][4 * gg + 2] + s2);
;           Sx[mt][4 * gg + 1] = __expf(Sx[mt][4 * gg + 1] + s1);
;           Sx[mt][4 * gg + 0] = __expf(Sx[mt][4 * gg + 0] + s0);
;         }
;         carry += tot;
;       }
	v_pk_add_f32 v[0:1], v[154:155], v[156:157]
	s_nop 0
	v_pk_add_f32 v[0:1], v[0:1], v[160:161]
	s_nop 0
	v_pk_add_f32 v[70:71], v[144:145], v[0:1]
	s_nop 0
	v_add_f32_e32 v0, v70, v1
	v_add_f32_e32 v0, v167, v0
	v_add_f32_e32 v1, v96, v0
	v_add_f32_e32 v0, v69, v0
	v_mul_f32_e32 v0, 0x3fb8aa3b, v0
	v_exp_f32_e32 v3, v0
	v_add_f32_e32 v0, v68, v1
	v_add_f32_e32 v7, v95, v1
	v_mul_f32_e32 v0, 0x3fb8aa3b, v0
	v_exp_f32_e32 v2, v0
	v_add_f32_e32 v0, v67, v7
	v_add_f32_e32 v14, v94, v7
	v_mul_f32_e32 v0, 0x3fb8aa3b, v0
	v_exp_f32_e32 v1, v0
	v_add_f32_e32 v0, v66, v14
	v_add_f32_e32 v7, v70, v161
	v_cndmask_b32_e32 v14, 0, v157, vcc
	v_add_f32_e32 v7, v14, v7
	v_add_f32_e32 v14, v89, v7
	v_add_f32_e32 v6, v6, v7
	v_add_f32_e32 v5, v5, v14
	v_add_f32_e32 v66, v87, v14
	v_mul_f32_e32 v6, 0x3fb8aa3b, v6
	v_mul_f32_e32 v5, 0x3fb8aa3b, v5
	v_exp_f32_e32 v7, v6
	v_exp_f32_e32 v6, v5
	v_add_f32_e32 v5, v8, v66
	v_add_f32_e32 v8, v159, v70
	v_cndmask_b32_e32 v14, 0, v153, vcc
	v_add_f32_e32 v8, v14, v8
	v_add_f32_e32 v14, v151, v8
	v_add_f32_e32 v8, v11, v8
	v_mul_f32_e32 v8, 0x3fb8aa3b, v8
	v_exp_f32_e32 v11, v8
	v_add_f32_e32 v8, v10, v14
	v_add_f32_e32 v67, v85, v66
	v_add_f32_e32 v66, v149, v14
	v_mul_f32_e32 v8, 0x3fb8aa3b, v8
	v_exp_f32_e32 v10, v8
	v_add_f32_e32 v8, v9, v66
	v_add_f32_e32 v4, v4, v67
	v_add_f32_e32 v67, v147, v66
	v_mul_f32_e32 v8, 0x3fb8aa3b, v8
	v_exp_f32_e32 v9, v8
	v_add_f32_e32 v8, v12, v67
	v_add_f32_e32 v12, 0, v70
	v_cndmask_b32_e32 v14, 0, v15, vcc
	v_add_f32_e32 v12, v14, v12
	v_add_f32_e32 v14, v165, v12
	v_add_f32_e32 v12, v166, v12
	v_mul_f32_e32 v12, 0x3fb8aa3b, v12
	v_exp_f32_e32 v15, v12
	v_add_f32_e32 v12, v164, v14
	v_add_f32_e32 v66, v163, v14
	v_mul_f32_e32 v12, 0x3fb8aa3b, v12
	v_exp_f32_e32 v14, v12
	v_add_f32_e32 v12, v97, v66
	v_add_f32_e32 v67, v13, v66
	v_mul_f32_e32 v12, 0x3fb8aa3b, v12
	v_exp_f32_e32 v13, v12
	v_add_f32_e32 v12, v162, v67
	v_mul_f32_e32 v0, 0x3fb8aa3b, v0
	v_mul_f32_e32 v5, 0x3fb8aa3b, v5
	v_mul_f32_e32 v4, 0x3fb8aa3b, v4
	v_mul_f32_e32 v8, 0x3fb8aa3b, v8
	v_mul_f32_e32 v12, 0x3fb8aa3b, v12
	v_exp_f32_e32 v0, v0
	v_exp_f32_e32 v5, v5
	v_exp_f32_e32 v4, v4
	v_exp_f32_e32 v8, v8
	v_exp_f32_e32 v12, v12
	v_add_f32_e32 v144, v70, v71
.LBB0_280:
	s_andn2_saveexec_b64 s[6:7], s[38:39]
	s_cbranch_execz .LBB0_282
	v_add_f32_e32 v0, 1.0, v243
	v_mov_b32_e32 v30, v91
	v_max_f32_e32 v165, 0, v165
	v_log_f32_e32 v0, v0
	v_max_f32_e32 v161, 0, v161
	v_max_f32_e32 v159, 0, v159
	v_max_f32_e32 v157, 0, v157
	v_mul_f32_e32 v1, 0x3f317217, v0
	v_fma_f32 v1, v0, s77, -v1
	v_fmac_f32_e32 v1, 0x3377d1cf, v0
	v_fmac_f32_e32 v1, 0x3f317217, v0
	v_max_f32_e32 v155, 0, v155
	v_mov_b32_e32 v0, v1
	v_add_f32_e32 v1, 1.0, v239
	v_log_f32_e32 v1, v1
	s_nop 0
	v_mul_f32_e32 v2, 0x3f317217, v1
	v_fma_f32 v2, v1, s77, -v2
	v_fmac_f32_e32 v2, 0x3377d1cf, v1
	v_fmac_f32_e32 v2, 0x3f317217, v1
	v_add_f32_e32 v1, 1.0, v205
	v_log_f32_e32 v1, v1
	s_nop 0
	v_mul_f32_e32 v4, 0x3f317217, v1
	v_fma_f32 v4, v1, s77, -v4
	v_fmac_f32_e32 v4, 0x3377d1cf, v1
	v_fmac_f32_e32 v4, 0x3f317217, v1
	v_add_f32_e32 v1, 1.0, v202
	v_log_f32_e32 v1, v1
	s_nop 0
	v_mul_f32_e32 v6, 0x3f317217, v1
	v_fma_f32 v6, v1, s77, -v6
	v_fmac_f32_e32 v6, 0x3377d1cf, v1
	v_fmac_f32_e32 v6, 0x3f317217, v1
	v_add_f32_e32 v1, 1.0, v201
	v_log_f32_e32 v1, v1
	s_nop 0
	v_mul_f32_e32 v8, 0x3f317217, v1
	v_fma_f32 v8, v1, s77, -v8
	v_fmac_f32_e32 v8, 0x3377d1cf, v1
	v_fmac_f32_e32 v8, 0x3f317217, v1
	v_add_f32_e32 v1, 1.0, v200
	v_log_f32_e32 v1, v1
	s_nop 0
	v_mul_f32_e32 v10, 0x3f317217, v1
	v_fma_f32 v10, v1, s77, -v10
	v_fmac_f32_e32 v10, 0x3377d1cf, v1
	v_fmac_f32_e32 v10, 0x3f317217, v1
	v_add_f32_e32 v1, 1.0, v199
	v_log_f32_e32 v1, v1
	s_nop 0
	v_mul_f32_e32 v12, 0x3f317217, v1
	v_fma_f32 v12, v1, s77, -v12
	v_fmac_f32_e32 v12, 0x3377d1cf, v1
	v_fmac_f32_e32 v12, 0x3f317217, v1
	v_add_f32_e32 v1, 1.0, v198
	v_log_f32_e32 v1, v1
	s_nop 0
	v_mul_f32_e32 v14, 0x3f317217, v1
	v_fma_f32 v14, v1, s77, -v14
	v_fmac_f32_e32 v14, 0x3377d1cf, v1
	v_fmac_f32_e32 v14, 0x3f317217, v1
	v_add_f32_e32 v1, 1.0, v197
	v_log_f32_e32 v1, v1
	s_nop 0
	v_mul_f32_e32 v16, 0x3f317217, v1
	v_fma_f32 v16, v1, s77, -v16
	v_fmac_f32_e32 v16, 0x3377d1cf, v1
	v_fmac_f32_e32 v16, 0x3f317217, v1
	v_add_f32_e32 v1, 1.0, v196
	v_log_f32_e32 v1, v1
	s_nop 0
	v_mul_f32_e32 v18, 0x3f317217, v1
	v_fma_f32 v18, v1, s77, -v18
	v_fmac_f32_e32 v18, 0x3377d1cf, v1
	v_fmac_f32_e32 v18, 0x3f317217, v1
	v_add_f32_e32 v1, 1.0, v195
	v_log_f32_e32 v1, v1
	s_nop 0
	v_mul_f32_e32 v17, 0x3f317217, v1
	v_fma_f32 v17, v1, s77, -v17
	v_fmac_f32_e32 v17, 0x3377d1cf, v1
	v_fmac_f32_e32 v17, 0x3f317217, v1
	v_add_f32_e32 v1, 1.0, v194
	v_pk_add_f32 v[24:25], v[172:173], v[16:17]
	v_log_f32_e32 v1, v1
	s_nop 0
	v_mul_f32_e32 v19, 0x3f317217, v1
	v_fma_f32 v19, v1, s77, -v19
	v_fmac_f32_e32 v19, 0x3377d1cf, v1
	v_fmac_f32_e32 v19, 0x3f317217, v1
	v_add_f32_e32 v1, 1.0, v193
	v_pk_add_f32 v[26:27], v[170:171], v[18:19]
	v_log_f32_e32 v1, v1
	v_pk_add_f32 v[16:17], v[26:27], v[24:25] neg_lo:[1,1] neg_hi:[1,1]
	v_mul_f32_e32 v20, 0x3f317217, v1
	v_fma_f32 v20, v1, s77, -v20
	v_fmac_f32_e32 v20, 0x3377d1cf, v1
	v_fmac_f32_e32 v20, 0x3f317217, v1
	v_pk_add_f32 v[16:17], v[16:17], v[16:17] op_sel:[0,1] op_sel_hi:[1,0]
	ds_bpermute_b32 v18, v181, v16
	v_add_f32_e32 v1, 1.0, v192
	s_waitcnt lgkmcnt(0)
; DI int crow(int i, int h) { return (i & 3) + 8 * (i >> 2) + 4 * h; }
; DI float shx32(float v) { return __shfl_xor(v, 32); }
; template <bool MASKED>
; DI void sb_weights(f32x16 (&Sx)[2], float& carry, int kt, int t, int h) {
;     ...
;         for (int i = 0; i < 16; ++i) {
;           const float z = Sx[mt][i];
;           const bool ok = !MASKED || (kt * 64 + mt * 32 + crow(i, h) < t);
;           const float sp = fmaxf(z, 0.f) + __logf(1.f + __expf(-fabsf(z)));
;           L[i] = ok ? -sp : 0.f;
;           Sx[mt][i] = ok ? (z - sp) : NEG;
;         }
;         float G[4], Go[4];
; #pragma unroll
;         for (int gg = 0; gg < 4; ++gg) { G[gg] = (L[4 * gg] + L[4 * gg + 1]) + (L[4 * gg + 2] + L[4 * gg + 3]); Go[gg] = shx32(G[gg]); }
;         float T[4];
;         T[3] = 0.f; T[2] = G[3] + Go[3]; T[1] = T[2] + (G[2] + Go[2]); T[0] = T[1] + (G[1] + Go[1]);
;         const float tot = T[0] + (G[0] + Go[0]);
; #pragma unroll
;         for (int gg = 0; gg < 4; ++gg) {
;           const float s3 = carry + T[gg] + (h ? 0.f : Go[gg]);
;           const float s2 = s3 + L[4 * gg + 3], s1 = s2 + L[4 * gg + 2], s0 = s1 + L[4 * gg + 1];
;           Sx[mt][4 * gg + 3] = __expf(Sx[mt][4 * gg + 3] + s3);
;           Sx[mt][4 * gg + 2] = __expf(Sx[mt][4 * gg + 2] + s2);
;           Sx[mt][4 * gg + 1] = __expf(Sx[mt][4 * gg + 1] + s1);
;           Sx[mt][4 * gg + 0] = __expf(Sx[mt][4 * gg + 0] + s0);
;         }
	v_cndmask_b32_e32 v9, 0, v18, vcc
	v_log_f32_e32 v1, v1
	s_nop 0
	v_mul_f32_e32 v22, 0x3f317217, v1
	v_fma_f32 v22, v1, s77, -v22
	v_fmac_f32_e32 v22, 0x3377d1cf, v1
	v_fmac_f32_e32 v22, 0x3f317217, v1
	v_add_f32_e32 v1, 1.0, v191
	v_log_f32_e32 v1, v1
	s_nop 0
	v_mul_f32_e32 v21, 0x3f317217, v1
	v_fma_f32 v21, v1, s77, -v21
	v_fmac_f32_e32 v21, 0x3377d1cf, v1
	v_fmac_f32_e32 v21, 0x3f317217, v1
	v_add_f32_e32 v1, 1.0, v190
	v_pk_add_f32 v[20:21], v[168:169], v[20:21]
	v_log_f32_e32 v1, v1
	s_nop 0
	v_mul_f32_e32 v23, 0x3f317217, v1
	v_fma_f32 v23, v1, s77, -v23
	v_fmac_f32_e32 v23, 0x3377d1cf, v1
	v_fmac_f32_e32 v23, 0x3f317217, v1
	v_pk_add_f32 v[22:23], v[166:167], v[22:23]
	v_sub_f32_e32 v1, v93, v27
	v_pk_add_f32 v[28:29], v[22:23], v[20:21] neg_lo:[1,1] neg_hi:[1,1]
	v_sub_f32_e32 v3, v97, v23
	v_add_f32_e32 v5, v28, v29
	ds_bpermute_b32 v7, v181, v5
	v_mov_b32_e32 v28, v25
	v_mov_b32_e32 v29, v27
	v_mov_b32_e32 v27, v25
	v_mov_b32_e32 v25, v26
	s_waitcnt lgkmcnt(0)
	v_add_f32_e32 v166, v5, v7
	v_add_f32_e32 v5, v144, v166
	v_add_f32_e32 v93, v9, v5
	v_pk_add_f32 v[28:29], v[92:93], v[28:29] neg_lo:[0,1] neg_hi:[0,1]
	v_add_f32_e32 v1, v1, v93
	v_mov_b32_e32 v31, v29
	v_mul_f32_e32 v1, 0x3fb8aa3b, v1
	v_pk_add_f32 v[30:31], v[30:31], v[26:27] neg_lo:[0,1] neg_hi:[0,1]
	v_exp_f32_e32 v27, v1
	v_add_f32_e32 v1, v28, v29
	v_mul_f32_e32 v1, 0x3fb8aa3b, v1
	v_mov_b32_e32 v91, v31
	v_exp_f32_e32 v26, v1
	v_add_f32_e32 v1, v30, v31
	v_pk_add_f32 v[90:91], v[90:91], v[24:25] neg_lo:[0,1] neg_hi:[0,1]
	v_mul_f32_e32 v1, 0x3fb8aa3b, v1
	v_exp_f32_e32 v25, v1
	v_add_f32_e32 v1, v90, v91
	v_mul_f32_e32 v1, 0x3fb8aa3b, v1
	v_exp_f32_e32 v24, v1
	v_cndmask_b32_e32 v1, 0, v7, vcc
	v_add_f32_e32 v97, v188, v1
	v_mov_b32_e32 v28, v21
	v_mov_b32_e32 v29, v23
	v_pk_add_f32 v[28:29], v[96:97], v[28:29] neg_lo:[0,1] neg_hi:[0,1]
	v_add_f32_e32 v1, v3, v97
	v_mov_b32_e32 v30, v95
	v_mov_b32_e32 v31, v29
	v_mov_b32_e32 v23, v21
	v_mul_f32_e32 v1, 0x3fb8aa3b, v1
	v_pk_add_f32 v[90:91], v[30:31], v[22:23] neg_lo:[0,1] neg_hi:[0,1]
	v_exp_f32_e32 v31, v1
	v_add_f32_e32 v1, v28, v29
	v_mul_f32_e32 v1, 0x3fb8aa3b, v1
	v_mov_b32_e32 v95, v91
	v_mov_b32_e32 v21, v22
	v_exp_f32_e32 v30, v1
	v_add_f32_e32 v1, v90, v91
	v_pk_add_f32 v[20:21], v[94:95], v[20:21] neg_lo:[0,1] neg_hi:[0,1]
	v_mul_f32_e32 v1, 0x3fb8aa3b, v1
	v_exp_f32_e32 v29, v1
	v_add_f32_e32 v1, v20, v21
	v_mul_f32_e32 v1, 0x3fb8aa3b, v1
	v_exp_f32_e32 v28, v1
	v_add_f32_e32 v1, 1.0, v189
	v_log_f32_e32 v1, v1
	s_nop 0
	v_mul_f32_e32 v20, 0x3f317217, v1
	v_fma_f32 v20, v1, s77, -v20
	v_fmac_f32_e32 v20, 0x3377d1cf, v1
	v_fmac_f32_e32 v20, 0x3f317217, v1
	v_add_f32_e32 v1, 1.0, v187
	v_log_f32_e32 v1, v1
	s_nop 0
	v_mul_f32_e32 v22, 0x3f317217, v1
	v_fma_f32 v22, v1, s77, -v22
	v_fmac_f32_e32 v22, 0x3377d1cf, v1
	v_fmac_f32_e32 v22, 0x3f317217, v1
	v_add_f32_e32 v1, 1.0, v186
	v_log_f32_e32 v1, v1
	s_nop 0
	v_mul_f32_e32 v21, 0x3f317217, v1
	v_fma_f32 v21, v1, s77, -v21
	v_fmac_f32_e32 v21, 0x3377d1cf, v1
	v_fmac_f32_e32 v21, 0x3f317217, v1
	v_exp_f32_e32 v1, v185
	v_pk_add_f32 v[96:97], v[162:163], v[20:21]
	v_add_f32_e32 v1, 1.0, v1
	v_log_f32_e32 v1, v1
	s_nop 0
	v_mul_f32_e32 v23, 0x3f317217, v1
	v_fma_f32 v23, v1, s77, -v23
	v_fmac_f32_e32 v23, 0x3377d1cf, v1
	v_fmac_f32_e32 v23, 0x3f317217, v1
	v_exp_f32_e32 v1, v184
	v_pk_add_f32 v[162:163], v[164:165], v[22:23]
	v_add_f32_e32 v1, 1.0, v1
	v_pk_add_f32 v[20:21], v[162:163], v[96:97] neg_lo:[1,1] neg_hi:[1,1]
	v_sub_f32_e32 v170, v69, v163
	v_log_f32_e32 v1, v1
	s_nop 0
	v_mul_f32_e32 v3, 0x3f317217, v1
	v_fma_f32 v3, v1, s77, -v3
	v_fmac_f32_e32 v3, 0x3377d1cf, v1
	v_fmac_f32_e32 v3, 0x3f317217, v1
	v_mov_b32_e32 v1, v3
	v_exp_f32_e32 v3, v183
	v_pk_add_f32 v[160:161], v[160:161], v[0:1]
	v_add_f32_e32 v3, 1.0, v3
	v_log_f32_e32 v3, v3
	s_nop 0
	v_mul_f32_e32 v5, 0x3f317217, v3
	v_fma_f32 v5, v3, s77, -v5
	v_fmac_f32_e32 v5, 0x3377d1cf, v3
	v_fmac_f32_e32 v5, 0x3f317217, v3
	v_mov_b32_e32 v3, v5
	v_exp_f32_e32 v5, v182
	v_pk_add_f32 v[158:159], v[158:159], v[2:3]
	v_add_f32_e32 v5, 1.0, v5
	v_pk_add_f32 v[0:1], v[158:159], v[160:161] neg_lo:[1,1] neg_hi:[1,1]
	v_log_f32_e32 v5, v5
	s_nop 0
	v_mul_f32_e32 v7, 0x3f317217, v5
	v_fma_f32 v7, v5, s77, -v7
	v_fmac_f32_e32 v7, 0x3377d1cf, v5
	v_fmac_f32_e32 v7, 0x3f317217, v5
	v_mov_b32_e32 v5, v7
	v_exp_f32_e32 v7, v153
	v_max_f32_e32 v153, 0, v151
	v_max_f32_e32 v151, 0, v147
	v_pk_add_f32 v[4:5], v[156:157], v[4:5]
	v_add_f32_e32 v7, 1.0, v7
	v_log_f32_e32 v7, v7
	s_nop 0
	v_mul_f32_e32 v9, 0x3f317217, v7
	v_fma_f32 v9, v7, s77, -v9
	v_fmac_f32_e32 v9, 0x3377d1cf, v7
	v_fmac_f32_e32 v9, 0x3f317217, v7
	v_mov_b32_e32 v7, v9
	v_exp_f32_e32 v9, v149
	v_pk_add_f32 v[6:7], v[154:155], v[6:7]
	v_add_f32_e32 v9, 1.0, v9
	v_pk_add_f32 v[2:3], v[6:7], v[4:5] neg_lo:[1,1] neg_hi:[1,1]
	v_sub_f32_e32 v171, v85, v6
	v_log_f32_e32 v9, v9
	v_pk_add_f32 v[0:1], v[0:1], v[2:3]
	ds_bpermute_b32 v2, v181, v0
	ds_bpermute_b32 v3, v181, v1
	v_mul_f32_e32 v11, 0x3f317217, v9
	v_fma_f32 v11, v9, s77, -v11
	v_fmac_f32_e32 v11, 0x3377d1cf, v9
	v_fmac_f32_e32 v11, 0x3f317217, v9
	s_waitcnt lgkmcnt(1)
	v_cndmask_b32_e32 v85, 0, v2, vcc
	s_waitcnt lgkmcnt(0)
; DI int crow(int i, int h) { return (i & 3) + 8 * (i >> 2) + 4 * h; }
; DI float shx32(float v) { return __shfl_xor(v, 32); }
; template <bool MASKED>
; DI void sb_weights(f32x16 (&Sx)[2], float& carry, int kt, int t, int h) {
;     ...
;         for (int i = 0; i < 16; ++i) {
;           const float z = Sx[mt][i];
;           const bool ok = !MASKED || (kt * 64 + mt * 32 + crow(i, h) < t);
;           const float sp = fmaxf(z, 0.f) + __logf(1.f + __expf(-fabsf(z)));
;           L[i] = ok ? -sp : 0.f;
;           Sx[mt][i] = ok ? (z - sp) : NEG;
;         }
;         float G[4], Go[4];
; #pragma unroll
;         for (int gg = 0; gg < 4; ++gg) { G[gg] = (L[4 * gg] + L[4 * gg + 1]) + (L[4 * gg + 2] + L[4 * gg + 3]); Go[gg] = shx32(G[gg]); }
;         float T[4];
;         T[3] = 0.f; T[2] = G[3] + Go[3]; T[1] = T[2] + (G[2] + Go[2]); T[0] = T[1] + (G[1] + Go[1]);
	v_pk_add_f32 v[0:1], v[0:1], v[2:3]
	v_mov_b32_e32 v9, v11
	v_exp_f32_e32 v11, v145
	v_pk_add_f32 v[8:9], v[152:153], v[8:9]
	v_add_f32_e32 v11, 1.0, v11
	v_mov_b32_e32 v156, v8
	v_log_f32_e32 v11, v11
	s_nop 0
	v_mul_f32_e32 v13, 0x3f317217, v11
	v_fma_f32 v13, v11, s77, -v13
	v_fmac_f32_e32 v13, 0x3377d1cf, v11
	v_fmac_f32_e32 v13, 0x3f317217, v11
	v_mov_b32_e32 v11, v13
	v_max_f32_e32 v149, 0, v76
	v_mul_f32_e64 v13, |v76|, s76
	v_exp_f32_e32 v13, v13
	v_pk_add_f32 v[10:11], v[150:151], v[10:11]
	v_mov_b32_e32 v150, v160
	v_mov_b32_e32 v151, v158
	v_add_f32_e32 v13, 1.0, v13
	v_mov_b32_e32 v154, v10
	v_mov_b32_e32 v157, v10
	v_log_f32_e32 v13, v13
	s_nop 0
	v_mul_f32_e32 v15, 0x3f317217, v13
	v_fma_f32 v15, v13, s77, -v15
	v_fmac_f32_e32 v15, 0x3377d1cf, v13
	v_fmac_f32_e32 v15, 0x3f317217, v13
	v_mov_b32_e32 v13, v15
	v_max_f32_e32 v147, 0, v77
	v_mul_f32_e64 v15, |v77|, s76
	v_exp_f32_e32 v15, v15
	v_pk_add_f32 v[12:13], v[148:149], v[12:13]
	v_mov_b32_e32 v148, v158
	v_mov_b32_e32 v149, v4
	v_add_f32_e32 v15, 1.0, v15
	v_mov_b32_e32 v152, v12
	v_mov_b32_e32 v155, v12
	v_log_f32_e32 v15, v15
	v_mov_b32_e32 v158, v161
	v_mul_f32_e32 v17, 0x3f317217, v15
	v_fma_f32 v17, v15, s77, -v17
	v_fmac_f32_e32 v17, 0x3377d1cf, v15
	v_fmac_f32_e32 v17, 0x3f317217, v15
	v_mov_b32_e32 v15, v17
	v_max_f32_e32 v90, 0, v78
	v_mul_f32_e64 v17, |v78|, s76
	v_exp_f32_e32 v17, v17
	v_pk_add_f32 v[14:15], v[146:147], v[14:15]
	v_mov_b32_e32 v147, v6
	v_pk_add_f32 v[22:23], v[14:15], v[12:13] neg_lo:[1,1] neg_hi:[1,1]
	v_add_f32_e32 v17, 1.0, v17
	v_cndmask_b32_e32 v6, 0, v3, vcc
	v_mov_b32_e32 v146, v4
	v_log_f32_e32 v17, v17
	v_sub_f32_e32 v172, v89, v14
	v_mov_b32_e32 v153, v14
	v_sub_f32_e32 v160, v77, v15
	v_mul_f32_e32 v92, 0x3f317217, v17
	v_fma_f32 v92, v17, s77, -v92
	v_fmac_f32_e32 v92, 0x3377d1cf, v17
	v_fmac_f32_e32 v92, 0x3f317217, v17
	v_mov_b32_e32 v14, v13
	v_max_f32_e32 v91, 0, v79
	v_mul_f32_e64 v17, |v79|, s76
	v_exp_f32_e32 v17, v17
	s_nop 0
	v_add_f32_e32 v17, 1.0, v17
	v_log_f32_e32 v17, v17
	s_nop 0
	v_mul_f32_e32 v93, 0x3f317217, v17
	v_fma_f32 v93, v17, s77, -v93
	v_fmac_f32_e32 v93, 0x3377d1cf, v17
	v_fmac_f32_e32 v93, 0x3f317217, v17
	v_max_f32_e32 v94, 0, v80
	v_mul_f32_e64 v17, |v80|, s76
	v_exp_f32_e32 v17, v17
	v_pk_add_f32 v[90:91], v[90:91], v[92:93]
	v_add_f32_e32 v17, 1.0, v17
	v_log_f32_e32 v17, v17
	s_nop 0
	v_mul_f32_e32 v168, 0x3f317217, v17
	v_fma_f32 v168, v17, s77, -v168
	v_fmac_f32_e32 v168, 0x3377d1cf, v17
	v_fmac_f32_e32 v168, 0x3f317217, v17
	v_max_f32_e32 v95, 0, v81
	v_mul_f32_e64 v17, |v81|, s76
	v_exp_f32_e32 v17, v17
	s_nop 0
	v_add_f32_e32 v17, 1.0, v17
	v_log_f32_e32 v17, v17
	s_nop 0
	v_mul_f32_e32 v169, 0x3f317217, v17
	v_fma_f32 v169, v17, s77, -v169
	v_fmac_f32_e32 v169, 0x3377d1cf, v17
	v_fmac_f32_e32 v169, 0x3f317217, v17
	v_add_f32_e32 v17, v20, v21
	ds_bpermute_b32 v19, v181, v17
	v_pk_add_f32 v[94:95], v[94:95], v[168:169]
	v_pk_add_f32 v[20:21], v[10:11], v[8:9] neg_lo:[1,1] neg_hi:[1,1]
	v_sub_f32_e32 v8, v73, v7
	v_pk_add_f32 v[20:21], v[20:21], v[22:23]
	s_waitcnt lgkmcnt(0)
	v_add_f32_e32 v145, v17, v19
	v_cndmask_b32_e32 v69, 0, v19, vcc
	v_sub_f32_e64 v19, -v95, v94
	v_sub_f32_e64 v17, -v91, v90
	v_pk_add_f32 v[2:3], v[16:17], v[18:19]
	ds_bpermute_b32 v22, v181, v20
	ds_bpermute_b32 v23, v181, v21
	ds_bpermute_b32 v167, v181, v3
	v_mov_b32_e32 v16, v83
	v_sub_f32_e32 v168, v81, v95
	s_waitcnt lgkmcnt(2)
	v_cndmask_b32_e32 v4, 0, v22, vcc
	s_waitcnt lgkmcnt(1)
	v_pk_add_f32 v[20:21], v[20:21], v[22:23]
	s_waitcnt lgkmcnt(0)
; DI float shx32(float v) { return __shfl_xor(v, 32); }
; template <bool MASKED>
; DI void sb_weights(f32x16 (&Sx)[2], float& carry, int kt, int t, int h) {
;     ...
;         float G[4], Go[4];
; #pragma unroll
;         for (int gg = 0; gg < 4; ++gg) { G[gg] = (L[4 * gg] + L[4 * gg + 1]) + (L[4 * gg + 2] + L[4 * gg + 3]); Go[gg] = shx32(G[gg]); }
;         float T[4];
;         T[3] = 0.f; T[2] = G[3] + Go[3]; T[1] = T[2] + (G[2] + Go[2]); T[0] = T[1] + (G[1] + Go[1]);
;         const float tot = T[0] + (G[0] + Go[0]);
; #pragma unroll
;         for (int gg = 0; gg < 4; ++gg) {
;           const float s3 = carry + T[gg] + (h ? 0.f : Go[gg]);
;           const float s2 = s3 + L[4 * gg + 3], s1 = s2 + L[4 * gg + 2], s0 = s1 + L[4 * gg + 1];
;           Sx[mt][4 * gg + 3] = __expf(Sx[mt][4 * gg + 3] + s3);
;           Sx[mt][4 * gg + 2] = __expf(Sx[mt][4 * gg + 2] + s2);
;           Sx[mt][4 * gg + 1] = __expf(Sx[mt][4 * gg + 1] + s1);
;           Sx[mt][4 * gg + 0] = __expf(Sx[mt][4 * gg + 0] + s0);
;         }
;         carry += tot;
	v_pk_add_f32 v[92:93], v[2:3], v[166:167]
	v_cndmask_b32_e32 v10, 0, v23, vcc
	v_pk_add_f32 v[164:165], v[20:21], v[92:93]
	s_nop 0
	v_add_f32_e32 v2, v144, v164
	v_add_f32_e32 v85, v85, v2
	v_pk_add_f32 v[2:3], v[84:85], v[146:147] neg_lo:[0,1] neg_hi:[0,1]
	v_pk_add_f32 v[0:1], v[0:1], v[164:165]
	v_mov_b32_e32 v17, v3
	v_add_f32_e32 v2, v2, v3
	v_pk_add_f32 v[16:17], v[16:17], v[148:149] neg_lo:[0,1] neg_hi:[0,1]
	v_mul_f32_e32 v2, 0x3fb8aa3b, v2
	v_mov_b32_e32 v83, v17
	v_exp_f32_e32 v18, v2
	v_add_f32_e32 v2, v16, v17
	v_pk_add_f32 v[20:21], v[82:83], v[150:151] neg_lo:[0,1] neg_hi:[0,1]
	v_mul_f32_e32 v2, 0x3fb8aa3b, v2
	v_exp_f32_e32 v17, v2
	v_add_f32_e32 v2, v20, v21
	v_mul_f32_e32 v2, 0x3fb8aa3b, v2
	v_exp_f32_e32 v16, v2
	v_add_f32_e32 v2, v144, v92
	v_add_f32_e32 v89, v4, v2
	v_pk_add_f32 v[2:3], v[88:89], v[152:153] neg_lo:[0,1] neg_hi:[0,1]
	v_mov_b32_e32 v20, v87
	v_mov_b32_e32 v21, v3
	v_add_f32_e32 v2, v2, v3
	v_pk_add_f32 v[20:21], v[20:21], v[154:155] neg_lo:[0,1] neg_hi:[0,1]
	v_mul_f32_e32 v2, 0x3fb8aa3b, v2
	v_mov_b32_e32 v87, v21
	v_exp_f32_e32 v22, v2
	v_add_f32_e32 v2, v20, v21
	v_pk_add_f32 v[82:83], v[86:87], v[156:157] neg_lo:[0,1] neg_hi:[0,1]
	v_mul_f32_e32 v2, 0x3fb8aa3b, v2
	v_exp_f32_e32 v21, v2
	v_add_f32_e32 v2, v82, v83
	v_pk_add_f32 v[82:83], v[144:145], v[0:1]
	v_mul_f32_e32 v2, 0x3fb8aa3b, v2
	v_add_f32_e32 v0, v82, v1
	v_add_f32_e32 v69, v69, v0
	v_mov_b32_e32 v0, v97
	v_mov_b32_e32 v1, v163
	v_pk_add_f32 v[0:1], v[68:69], v[0:1] neg_lo:[0,1] neg_hi:[0,1]
	v_exp_f32_e32 v20, v2
	v_mov_b32_e32 v2, v67
	v_mov_b32_e32 v3, v1
	v_mov_b32_e32 v163, v97
	v_add_f32_e32 v12, v171, v85
	v_add_f32_e32 v4, v172, v89
	v_pk_add_f32 v[84:85], v[2:3], v[162:163] neg_lo:[0,1] neg_hi:[0,1]
	v_add_f32_e32 v2, v170, v69
	v_add_f32_e32 v0, v0, v1
	v_mul_f32_e32 v4, 0x3fb8aa3b, v4
	v_mul_f32_e32 v2, 0x3fb8aa3b, v2
	v_mul_f32_e32 v0, 0x3fb8aa3b, v0
	v_exp_f32_e32 v23, v4
	v_mov_b32_e32 v67, v85
	v_mov_b32_e32 v97, v162
	v_exp_f32_e32 v3, v2
	v_exp_f32_e32 v2, v0
	v_add_f32_e32 v0, v84, v85
	v_add_f32_e32 v4, v82, v165
	v_pk_add_f32 v[66:67], v[66:67], v[96:97] neg_lo:[0,1] neg_hi:[0,1]
	v_mul_f32_e32 v0, 0x3fb8aa3b, v0
	v_add_f32_e32 v73, v6, v4
	v_mov_b32_e32 v6, v5
	v_exp_f32_e32 v1, v0
	v_add_f32_e32 v0, v66, v67
	v_pk_add_f32 v[66:67], v[72:73], v[6:7] neg_lo:[0,1] neg_hi:[0,1]
	v_mov_b32_e32 v6, v71
	v_mov_b32_e32 v7, v67
	v_mov_b32_e32 v4, v159
	v_pk_add_f32 v[4:5], v[6:7], v[4:5] neg_lo:[0,1] neg_hi:[0,1]
	v_add_f32_e32 v6, v8, v73
	v_add_f32_e32 v8, v93, v82
	v_add_f32_e32 v77, v10, v8
	v_mul_f32_e32 v12, 0x3fb8aa3b, v12
	v_mul_f32_e32 v6, 0x3fb8aa3b, v6
	v_pk_add_f32 v[14:15], v[76:77], v[14:15] neg_lo:[0,1] neg_hi:[0,1]
	v_exp_f32_e32 v19, v12
	v_exp_f32_e32 v7, v6
	v_add_f32_e32 v6, v66, v67
	v_mov_b32_e32 v66, v75
	v_mov_b32_e32 v67, v15
	v_mov_b32_e32 v12, v11
	v_pk_add_f32 v[12:13], v[66:67], v[12:13] neg_lo:[0,1] neg_hi:[0,1]
	v_add_f32_e32 v8, v160, v77
	v_mov_b32_e32 v75, v13
	v_mov_b32_e32 v10, v9
	v_mul_f32_e32 v8, 0x3fb8aa3b, v8
	v_pk_add_f32 v[66:67], v[74:75], v[10:11] neg_lo:[0,1] neg_hi:[0,1]
	v_exp_f32_e32 v11, v8
	v_add_f32_e32 v8, v14, v15
	v_mul_f32_e32 v8, 0x3fb8aa3b, v8
	v_exp_f32_e32 v10, v8
	v_add_f32_e32 v8, v12, v13
	v_add_f32_e32 v12, 0, v82
	v_cndmask_b32_e32 v13, 0, v167, vcc
	v_add_f32_e32 v81, v13, v12
	v_mul_f32_e32 v8, 0x3fb8aa3b, v8
	v_pk_add_f32 v[12:13], v[80:81], v[94:95] neg_lo:[0,1] neg_hi:[0,1]
	v_exp_f32_e32 v9, v8
	v_add_f32_e32 v8, v66, v67
	v_mov_b32_e32 v14, v79
	v_mov_b32_e32 v15, v13
	v_pk_mov_b32 v[66:67], v[90:91], v[94:95] op_sel:[1,0]
	v_add_f32_e32 v12, v12, v13
	v_pk_add_f32 v[66:67], v[14:15], v[66:67] neg_lo:[0,1] neg_hi:[0,1]
	v_add_f32_e32 v14, v168, v81
	v_mov_b32_e32 v71, v5
	v_add_f32_e32 v4, v4, v5
	v_mul_f32_e32 v14, 0x3fb8aa3b, v14
	v_mul_f32_e32 v12, 0x3fb8aa3b, v12
	v_pk_add_f32 v[68:69], v[70:71], v[158:159] neg_lo:[0,1] neg_hi:[0,1]
	v_mul_f32_e32 v4, 0x3fb8aa3b, v4
	v_mov_b32_e32 v79, v67
	v_exp_f32_e32 v15, v14
	v_exp_f32_e32 v14, v12
	v_add_f32_e32 v12, v66, v67
	v_exp_f32_e32 v5, v4
	v_add_f32_e32 v4, v68, v69
	v_pk_add_f32 v[68:69], v[78:79], v[90:91] neg_lo:[0,1] neg_hi:[0,1]
	v_mul_f32_e32 v12, 0x3fb8aa3b, v12
	v_exp_f32_e32 v13, v12
	v_add_f32_e32 v12, v68, v69
	v_mul_f32_e32 v0, 0x3fb8aa3b, v0
	v_mul_f32_e32 v6, 0x3fb8aa3b, v6
	v_mul_f32_e32 v4, 0x3fb8aa3b, v4
	v_mul_f32_e32 v8, 0x3fb8aa3b, v8
	v_mul_f32_e32 v12, 0x3fb8aa3b, v12
	v_exp_f32_e32 v0, v0
	v_exp_f32_e32 v6, v6
	v_exp_f32_e32 v4, v4
	v_exp_f32_e32 v8, v8
	v_exp_f32_e32 v12, v12
	v_add_f32_e32 v144, v82, v83
